# gMLP step B: the eight (mean,rstd) LDS reads issued together right after the step-A barrier instead of one read-wait per normalise block
# baseline (speedup 1.0000x reference)
; #define LAS __attribute__((address_space(3)))
; __device__ __forceinline__ u32x4 pack8(f32x4 a, f32x4 b) { u32x4 w; w.x = pk2(a[0], a[1]); w.y = pk2(a[2], a[3]); w.z = pk2(b[0], b[1]); w.w = pk2(b[2], b[3]); return w; }
; __device__ __forceinline__ void gmlp_task(LAS unsigned char* lds, const Params& p, const bf16_t* P, bf16_t* Y, const float* svg, float* ssb, int l, bool sample, int b, int g, int q, int tid, int wave, int lane, bool load_ws = true) {
;     ...
; #pragma unroll
;         for (int k = 0; k < 2; ++k) {
;             const int id = tid + 512 * k;
;             if (id >= L * 8) continue;
;             const int ch = id & 7, j = id >> 3;
;             const f32x2 mr = MUR[sub * 128 + j];
;             const float mean = mr.x, rstd = mr.y;
;             const u32x4 w = wraw[sub][k];
;             const f32x4 g0 = *(const f32x4*)(lg + ch * 8), g1 = *(const f32x4*)(lg + ch * 8 + 4), b0 = *(const f32x4*)(lb + ch * 8), b1 = *(const f32x4*)(lb + ch * 8 + 4);
;             f32x4 v0 = (f32x4){bf_lo(w.x), bf_hi(w.x), bf_lo(w.y), bf_hi(w.y)}, v1 = (f32x4){bf_lo(w.z), bf_hi(w.z), bf_lo(w.w), bf_hi(w.w)};
;             v0 = (v0 - mean) * rstd * g0 + b0; v1 = (v1 - mean) * rstd * g1 + b1;
;             if (sample) { float* dst = p.out + OUT_VGS + ((((size_t)l * 32 + cidx) * 32 + j) * 16 + g) * 64 + ch * 8; *(f32x4*)dst = v0; *(f32x4*)(dst + 4) = v1; }
;             *(LAS u32x4*)(VGT + j * 72 + ch * 8) = pack8(v0, v1);
.LBB0_478:
	s_or_b64 exec, exec, s[16:17]
	s_lshl_b64 s[16:17], s[0:1], 2
	s_add_u32 s18, s25, s16
	s_addc_u32 s19, s26, s17
	s_add_u32 s16, s23, s16
	s_addc_u32 s17, s24, s17
	v_lshlrev_b32_e32 v0, 2, v46
	v_and_b32_e32 v39, -8, v44
	s_waitcnt lgkmcnt(0)
	v_lshl_add_u64 v[36:37], s[18:19], 0, v[0:1]
	v_lshl_add_u64 v[34:35], s[16:17], 0, v[0:1]
	global_load_dwordx4 v[192:195], v[36:37], off offset:16
	global_load_dwordx4 v[196:199], v[36:37], off
	global_load_dwordx4 v[200:203], v[34:35], off offset:16
	global_load_dwordx4 v[204:207], v[34:35], off
	v_and_b32_e32 v124, 31, v42
	v_readlane_b32 s4, v253, 39
	s_lshl_b32 s11, s33, 7
	s_add_i32 s11, s11, s22
	s_nop 0
	v_or_b32_e32 v124, s4, v124
	v_add_u32_e32 v126, s11, v124
	v_ashrrev_i32_e32 v127, 31, v126
	v_lshl_add_u64 v[126:127], v[126:127], 2, s[64:65]
	global_load_dword v168, v[126:127], off
	v_add_u32_e32 v125, s44, v124
	v_mov_b64_e32 v[128:129], s[68:69]
	v_mad_u64_u32 v[128:129], vcc, v125, s73, v[128:129]
	v_readlane_b32 s4, v253, 40
	v_ashrrev_i32_e32 v130, 2, v42
	v_and_b32_e32 v130, -8, v130
	s_nop 0
	s_lshl_b32 s18, s4, 1
	s_mov_b32 s19, 0
	v_lshl_add_u64 v[128:129], s[0:1], 1, v[128:129]
	v_ashrrev_i32_e32 v131, 31, v130
	v_lshl_add_u64 v[128:129], v[128:129], 0, s[18:19]
	v_lshl_add_u64 v[128:129], v[130:131], 1, v[128:129]
	s_mov_b64 s[16:17], 0x1000
	v_lshl_add_u64 v[126:127], v[128:129], 0, s[16:17]
	global_load_dwordx4 v[164:167], v[126:127], off offset:1024
	s_mov_b64 s[16:17], 0x2000
	v_lshl_add_u64 v[126:127], v[128:129], 0, s[16:17]
	global_load_dwordx4 v[160:163], v[126:127], off offset:1024
	s_mov_b64 s[16:17], 0x1400
	v_lshl_add_u64 v[126:127], v[128:129], 0, s[16:17]
	global_load_dwordx4 v[156:159], v[126:127], off offset:32
	s_mov_b64 s[16:17], 0x2400
	v_lshl_add_u64 v[126:127], v[128:129], 0, s[16:17]
	global_load_dwordx4 v[152:155], v[126:127], off offset:32
	v_lshl_add_u32 v0, v46, 1, 0
	v_lshrrev_b32_e32 v38, 3, v44
	v_add_u32_e32 v39, 0, v39
	s_barrier
	v_add_u32_e32 v144, 0x1a800, v39
	v_and_b32_e32 v145, -8, v43
	v_add_u32_e32 v145, 0x1a800, v145
	ds_read_b64 v[170:171], v144
	ds_read_b64 v[172:173], v145
	ds_read_b64 v[174:175], v144 offset:1024
	ds_read_b64 v[176:177], v145 offset:1024
	ds_read_b64 v[178:179], v144 offset:2048
	ds_read_b64 v[180:181], v145 offset:2048
	ds_read_b64 v[182:183], v144 offset:3072
	ds_read_b64 v[146:147], v145 offset:3072
	s_and_saveexec_b64 s[16:17], s[42:43]
	s_cbranch_execz .LBB0_480
	s_waitcnt vmcnt(9)
	v_lshlrev_b32_e32 v44, 16, v30
	v_and_b32_e32 v62, 0xffff0000, v30
	v_lshlrev_b32_e32 v30, 16, v31
	v_and_b32_e32 v31, 0xffff0000, v31
	v_lshlrev_b32_e32 v63, 16, v32
	v_and_b32_e32 v64, 0xffff0000, v32
	v_lshlrev_b32_e32 v65, 16, v33
	v_and_b32_e32 v66, 0xffff0000, v33
	s_waitcnt lgkmcnt(0)
	v_sub_f32_e32 v31, v31, v170
	v_sub_f32_e32 v30, v30, v170
	v_sub_f32_e32 v33, v62, v170
	v_sub_f32_e32 v32, v44, v170
	v_pk_mul_f32 v[32:33], v[170:171], v[32:33] op_sel:[1,0]
	v_pk_mul_f32 v[30:31], v[170:171], v[30:31] op_sel:[1,0]
	s_waitcnt vmcnt(5)
	v_pk_fma_f32 v[52:53], v[198:199], v[30:31], v[206:207]
	v_pk_fma_f32 v[30:31], v[196:197], v[32:33], v[204:205]
	v_sub_f32_e32 v33, v66, v170
	v_sub_f32_e32 v32, v65, v170
	v_sub_f32_e32 v51, v64, v170
	v_sub_f32_e32 v50, v63, v170
	v_pk_mul_f32 v[50:51], v[170:171], v[50:51] op_sel:[1,0]
	v_pk_mul_f32 v[32:33], v[170:171], v[32:33] op_sel:[1,0]
	v_cvt_pk_bf16_f32 v30, v30, v31
	v_pk_fma_f32 v[40:41], v[194:195], v[32:33], v[202:203]
	v_pk_fma_f32 v[32:33], v[192:193], v[50:51], v[200:201]
	v_cvt_pk_bf16_f32 v31, v52, v53
	v_cvt_pk_bf16_f32 v32, v32, v33
	v_cvt_pk_bf16_f32 v33, v40, v41
	v_mad_u64_u32 v[40:41], s[18:19], v38, s89, v[0:1]
	ds_write_b128 v40, v[30:33]

; #define LAS __attribute__((address_space(3)))
; __device__ __forceinline__ u32x4 pack8(f32x4 a, f32x4 b) { u32x4 w; w.x = pk2(a[0], a[1]); w.y = pk2(a[2], a[3]); w.z = pk2(b[0], b[1]); w.w = pk2(b[2], b[3]); return w; }
; __device__ __forceinline__ void gmlp_task(LAS unsigned char* lds, const Params& p, const bf16_t* P, bf16_t* Y, const float* svg, float* ssb, int l, bool sample, int b, int g, int q, int tid, int wave, int lane, bool load_ws = true) {
;     ...
;             const int ch = id & 7, j = id >> 3;
;             const f32x2 mr = MUR[sub * 128 + j];
;             const float mean = mr.x, rstd = mr.y;
;             const u32x4 w = wraw[sub][k];
;             const f32x4 g0 = *(const f32x4*)(lg + ch * 8), g1 = *(const f32x4*)(lg + ch * 8 + 4), b0 = *(const f32x4*)(lb + ch * 8), b1 = *(const f32x4*)(lb + ch * 8 + 4);
;             f32x4 v0 = (f32x4){bf_lo(w.x), bf_hi(w.x), bf_lo(w.y), bf_hi(w.y)}, v1 = (f32x4){bf_lo(w.z), bf_hi(w.z), bf_lo(w.w), bf_hi(w.w)};
;             v0 = (v0 - mean) * rstd * g0 + b0; v1 = (v1 - mean) * rstd * g1 + b1;
;             if (sample) { float* dst = p.out + OUT_VGS + ((((size_t)l * 32 + cidx) * 32 + j) * 16 + g) * 64 + ch * 8; *(f32x4*)dst = v0; *(f32x4*)(dst + 4) = v1; }
;             *(LAS u32x4*)(VGT + j * 72 + ch * 8) = pack8(v0, v1);
.LBB0_487:
	v_lshlrev_b32_e32 v24, 16, v2
	v_and_b32_e32 v25, 0xffff0000, v2
	v_lshlrev_b32_e32 v2, 16, v3
	v_and_b32_e32 v3, 0xffff0000, v3
	v_lshlrev_b32_e32 v26, 16, v4
	v_and_b32_e32 v27, 0xffff0000, v4
	v_lshlrev_b32_e32 v28, 16, v5
	v_and_b32_e32 v29, 0xffff0000, v5
	s_waitcnt lgkmcnt(0)
	v_sub_f32_e32 v3, v3, v146
	v_sub_f32_e32 v2, v2, v146
	v_sub_f32_e32 v5, v25, v146
	v_sub_f32_e32 v4, v24, v146
	v_pk_mul_f32 v[4:5], v[146:147], v[4:5] op_sel:[1,0]
	v_pk_mul_f32 v[2:3], v[146:147], v[2:3] op_sel:[1,0]
	s_waitcnt vmcnt(5)
	v_pk_fma_f32 v[12:13], v[198:199], v[2:3], v[206:207]
	v_pk_fma_f32 v[2:3], v[196:197], v[4:5], v[204:205]
	v_sub_f32_e32 v5, v29, v146
	v_sub_f32_e32 v4, v28, v146
	v_sub_f32_e32 v11, v27, v146
	v_sub_f32_e32 v10, v26, v146
	v_pk_mul_f32 v[10:11], v[146:147], v[10:11] op_sel:[1,0]
	v_pk_mul_f32 v[4:5], v[146:147], v[4:5] op_sel:[1,0]
	v_cvt_pk_bf16_f32 v2, v2, v3
	v_pk_fma_f32 v[8:9], v[194:195], v[4:5], v[202:203]
	v_pk_fma_f32 v[4:5], v[192:193], v[10:11], v[200:201]
	v_cvt_pk_bf16_f32 v3, v12, v13
	v_cvt_pk_bf16_f32 v4, v4, v5
	v_cvt_pk_bf16_f32 v5, v8, v9
	v_mad_u64_u32 v[6:7], s[18:19], v30, s89, v[0:1]
	ds_write_b128 v6, v[2:5] offset:55296

; #define LAS __attribute__((address_space(3)))
; __device__ __forceinline__ u32x4 pack8(f32x4 a, f32x4 b) { u32x4 w; w.x = pk2(a[0], a[1]); w.y = pk2(a[2], a[3]); w.z = pk2(b[0], b[1]); w.w = pk2(b[2], b[3]); return w; }
; __device__ __forceinline__ void gmlp_task(LAS unsigned char* lds, const Params& p, const bf16_t* P, bf16_t* Y, const float* svg, float* ssb, int l, bool sample, int b, int g, int q, int tid, int wave, int lane, bool load_ws = true) {
;     ...
; #pragma unroll
;         for (int k = 0; k < 2; ++k) {
;             const int id = tid + 512 * k;
;             if (id >= L * 8) continue;
;             const int ch = id & 7, j = id >> 3;
;             const f32x2 mr = MUR[sub * 128 + j];
;             const float mean = mr.x, rstd = mr.y;
;             const u32x4 w = wraw[sub][k];
;             const f32x4 g0 = *(const f32x4*)(lg + ch * 8), g1 = *(const f32x4*)(lg + ch * 8 + 4), b0 = *(const f32x4*)(lb + ch * 8), b1 = *(const f32x4*)(lb + ch * 8 + 4);
;             f32x4 v0 = (f32x4){bf_lo(w.x), bf_hi(w.x), bf_lo(w.y), bf_hi(w.y)}, v1 = (f32x4){bf_lo(w.z), bf_hi(w.z), bf_lo(w.w), bf_hi(w.w)};
;             v0 = (v0 - mean) * rstd * g0 + b0; v1 = (v1 - mean) * rstd * g1 + b1;
;             if (sample) { float* dst = p.out + OUT_VGS + ((((size_t)l * 32 + cidx) * 32 + j) * 16 + g) * 64 + ch * 8; *(f32x4*)dst = v0; *(f32x4*)(dst + 4) = v1; }
;             *(LAS u32x4*)(VGT + j * 72 + ch * 8) = pack8(v0, v1);
.LBB0_504:
	v_lshlrev_b32_e32 v40, 16, v26
	v_and_b32_e32 v41, 0xffff0000, v26
	v_lshlrev_b32_e32 v26, 16, v27
	v_and_b32_e32 v27, 0xffff0000, v27
	v_lshlrev_b32_e32 v43, 16, v28
	v_and_b32_e32 v44, 0xffff0000, v28
	v_lshlrev_b32_e32 v62, 16, v29
	v_and_b32_e32 v63, 0xffff0000, v29
	s_waitcnt lgkmcnt(0)
	v_sub_f32_e32 v27, v27, v172
	v_sub_f32_e32 v26, v26, v172
	v_sub_f32_e32 v29, v41, v172
	v_sub_f32_e32 v28, v40, v172
	v_pk_mul_f32 v[28:29], v[172:173], v[28:29] op_sel:[1,0]
	v_pk_mul_f32 v[26:27], v[172:173], v[26:27] op_sel:[1,0]
	s_waitcnt vmcnt(5)
	v_pk_fma_f32 v[40:41], v[198:199], v[26:27], v[206:207]
	v_pk_fma_f32 v[26:27], v[196:197], v[28:29], v[204:205]
	v_sub_f32_e32 v29, v63, v172
	v_sub_f32_e32 v28, v62, v172
	v_sub_f32_e32 v51, v44, v172
	v_sub_f32_e32 v50, v43, v172
	v_pk_mul_f32 v[50:51], v[172:173], v[50:51] op_sel:[1,0]
	v_pk_mul_f32 v[28:29], v[172:173], v[28:29] op_sel:[1,0]
	v_cvt_pk_bf16_f32 v26, v26, v27
	v_pk_fma_f32 v[32:33], v[194:195], v[28:29], v[202:203]
	v_pk_fma_f32 v[28:29], v[192:193], v[50:51], v[200:201]
	v_cvt_pk_bf16_f32 v27, v40, v41
	v_cvt_pk_bf16_f32 v28, v28, v29
	v_cvt_pk_bf16_f32 v29, v32, v33
	v_mad_u64_u32 v[32:33], s[18:19], v30, s89, v[0:1]
	ds_write_b128 v32, v[26:29]
	s_or_b64 exec, exec, s[16:17]
	s_and_saveexec_b64 s[16:17], s[42:43]
	s_cbranch_execz .LBB0_482
.LBB0_505:
	v_lshlrev_b32_e32 v40, 16, v22
	v_and_b32_e32 v41, 0xffff0000, v22
	v_lshlrev_b32_e32 v22, 16, v23
	v_and_b32_e32 v23, 0xffff0000, v23
	v_lshlrev_b32_e32 v43, 16, v24
	v_and_b32_e32 v44, 0xffff0000, v24
	v_lshlrev_b32_e32 v58, 16, v25
	v_and_b32_e32 v59, 0xffff0000, v25
	s_waitcnt lgkmcnt(0)
	v_sub_f32_e32 v23, v23, v174
	v_sub_f32_e32 v22, v22, v174
	v_sub_f32_e32 v25, v41, v174
	v_sub_f32_e32 v24, v40, v174
	v_pk_mul_f32 v[24:25], v[174:175], v[24:25] op_sel:[1,0]
	v_pk_mul_f32 v[22:23], v[174:175], v[22:23] op_sel:[1,0]
	s_waitcnt vmcnt(5)
	v_pk_fma_f32 v[40:41], v[198:199], v[22:23], v[206:207]
	v_pk_fma_f32 v[22:23], v[196:197], v[24:25], v[204:205]
	v_sub_f32_e32 v25, v59, v174
	v_sub_f32_e32 v24, v58, v174
	v_sub_f32_e32 v47, v44, v174
	v_sub_f32_e32 v46, v43, v174
	v_pk_mul_f32 v[46:47], v[174:175], v[46:47] op_sel:[1,0]
	v_pk_mul_f32 v[24:25], v[174:175], v[24:25] op_sel:[1,0]
	v_cvt_pk_bf16_f32 v22, v22, v23
	v_pk_fma_f32 v[28:29], v[194:195], v[24:25], v[202:203]
	v_pk_fma_f32 v[24:25], v[192:193], v[46:47], v[200:201]
	v_cvt_pk_bf16_f32 v23, v40, v41
	v_cvt_pk_bf16_f32 v24, v24, v25
	v_cvt_pk_bf16_f32 v25, v28, v29
	v_mad_u64_u32 v[26:27], s[18:19], v38, s89, v[0:1]
	ds_write_b128 v26, v[22:25] offset:18432
	s_or_b64 exec, exec, s[16:17]
	s_and_saveexec_b64 s[16:17], s[40:41]
	s_cbranch_execz .LBB0_483
.LBB0_506:
	v_lshlrev_b32_e32 v40, 16, v18
	v_and_b32_e32 v41, 0xffff0000, v18
	v_lshlrev_b32_e32 v18, 16, v19
	v_and_b32_e32 v19, 0xffff0000, v19
	v_lshlrev_b32_e32 v43, 16, v20
	v_and_b32_e32 v44, 0xffff0000, v20
	v_lshlrev_b32_e32 v54, 16, v21
	v_and_b32_e32 v55, 0xffff0000, v21
	s_waitcnt lgkmcnt(0)
	v_sub_f32_e32 v19, v19, v176
	v_sub_f32_e32 v18, v18, v176
	v_sub_f32_e32 v21, v41, v176
	v_sub_f32_e32 v20, v40, v176
	v_pk_mul_f32 v[20:21], v[176:177], v[20:21] op_sel:[1,0]
	v_pk_mul_f32 v[18:19], v[176:177], v[18:19] op_sel:[1,0]
	s_waitcnt vmcnt(5)
	v_pk_fma_f32 v[28:29], v[198:199], v[18:19], v[206:207]
	v_pk_fma_f32 v[18:19], v[196:197], v[20:21], v[204:205]
	v_sub_f32_e32 v21, v55, v176
	v_sub_f32_e32 v20, v54, v176
	v_sub_f32_e32 v27, v44, v176
	v_sub_f32_e32 v26, v43, v176
	v_pk_mul_f32 v[26:27], v[176:177], v[26:27] op_sel:[1,0]
	v_pk_mul_f32 v[20:21], v[176:177], v[20:21] op_sel:[1,0]
	v_cvt_pk_bf16_f32 v18, v18, v19
	v_pk_fma_f32 v[24:25], v[194:195], v[20:21], v[202:203]
	v_pk_fma_f32 v[20:21], v[192:193], v[26:27], v[200:201]
	v_cvt_pk_bf16_f32 v19, v28, v29
	v_cvt_pk_bf16_f32 v20, v20, v21
	v_cvt_pk_bf16_f32 v21, v24, v25
	v_mad_u64_u32 v[22:23], s[18:19], v30, s89, v[0:1]
	ds_write_b128 v22, v[18:21] offset:18432
	s_or_b64 exec, exec, s[16:17]
	s_and_saveexec_b64 s[16:17], s[42:43]
	s_cbranch_execz .LBB0_484
; #define LAS __attribute__((address_space(3)))
; __device__ __forceinline__ u32x4 pack8(f32x4 a, f32x4 b) { u32x4 w; w.x = pk2(a[0], a[1]); w.y = pk2(a[2], a[3]); w.z = pk2(b[0], b[1]); w.w = pk2(b[2], b[3]); return w; }
; __device__ __forceinline__ void gmlp_task(LAS unsigned char* lds, const Params& p, const bf16_t* P, bf16_t* Y, const float* svg, float* ssb, int l, bool sample, int b, int g, int q, int tid, int wave, int lane, bool load_ws = true) {
;     ...
; #pragma unroll
;         for (int k = 0; k < 2; ++k) {
;             const int id = tid + 512 * k;
;             if (id >= L * 8) continue;
;             const int ch = id & 7, j = id >> 3;
;             const f32x2 mr = MUR[sub * 128 + j];
;             const float mean = mr.x, rstd = mr.y;
;             const u32x4 w = wraw[sub][k];
;             const f32x4 g0 = *(const f32x4*)(lg + ch * 8), g1 = *(const f32x4*)(lg + ch * 8 + 4), b0 = *(const f32x4*)(lb + ch * 8), b1 = *(const f32x4*)(lb + ch * 8 + 4);
;             f32x4 v0 = (f32x4){bf_lo(w.x), bf_hi(w.x), bf_lo(w.y), bf_hi(w.y)}, v1 = (f32x4){bf_lo(w.z), bf_hi(w.z), bf_lo(w.w), bf_hi(w.w)};
;             v0 = (v0 - mean) * rstd * g0 + b0; v1 = (v1 - mean) * rstd * g1 + b1;
;             if (sample) { float* dst = p.out + OUT_VGS + ((((size_t)l * 32 + cidx) * 32 + j) * 16 + g) * 64 + ch * 8; *(f32x4*)dst = v0; *(f32x4*)(dst + 4) = v1; }
;             *(LAS u32x4*)(VGT + j * 72 + ch * 8) = pack8(v0, v1);
.LBB0_507:
	v_lshlrev_b32_e32 v40, 16, v14
	v_and_b32_e32 v41, 0xffff0000, v14
	v_lshlrev_b32_e32 v14, 16, v15
	v_and_b32_e32 v15, 0xffff0000, v15
	v_lshlrev_b32_e32 v43, 16, v16
	v_and_b32_e32 v44, 0xffff0000, v16
	v_lshlrev_b32_e32 v50, 16, v17
	v_and_b32_e32 v51, 0xffff0000, v17
	s_waitcnt lgkmcnt(0)
	v_sub_f32_e32 v15, v15, v178
	v_sub_f32_e32 v14, v14, v178
	v_sub_f32_e32 v17, v41, v178
	v_sub_f32_e32 v16, v40, v178
	v_pk_mul_f32 v[16:17], v[178:179], v[16:17] op_sel:[1,0]
	v_pk_mul_f32 v[14:15], v[178:179], v[14:15] op_sel:[1,0]
	s_waitcnt vmcnt(5)
	v_pk_fma_f32 v[24:25], v[198:199], v[14:15], v[206:207]
	v_pk_fma_f32 v[14:15], v[196:197], v[16:17], v[204:205]
	v_sub_f32_e32 v17, v51, v178
	v_sub_f32_e32 v16, v50, v178
	v_sub_f32_e32 v23, v44, v178
	v_sub_f32_e32 v22, v43, v178
	v_pk_mul_f32 v[22:23], v[178:179], v[22:23] op_sel:[1,0]
	v_pk_mul_f32 v[16:17], v[178:179], v[16:17] op_sel:[1,0]
	v_cvt_pk_bf16_f32 v14, v14, v15
	v_pk_fma_f32 v[20:21], v[194:195], v[16:17], v[202:203]
	v_pk_fma_f32 v[16:17], v[192:193], v[22:23], v[200:201]
	v_cvt_pk_bf16_f32 v15, v24, v25
	v_cvt_pk_bf16_f32 v16, v16, v17
	v_cvt_pk_bf16_f32 v17, v20, v21
	v_mad_u64_u32 v[18:19], s[18:19], v38, s89, v[0:1]
	ds_write_b128 v18, v[14:17] offset:36864
	s_or_b64 exec, exec, s[16:17]
	s_and_saveexec_b64 s[16:17], s[40:41]
	s_cbranch_execz .LBB0_485
.LBB0_508:
	v_lshlrev_b32_e32 v40, 16, v10
	v_and_b32_e32 v41, 0xffff0000, v10
	v_lshlrev_b32_e32 v10, 16, v11
	v_and_b32_e32 v11, 0xffff0000, v11
	v_lshlrev_b32_e32 v43, 16, v12
	v_and_b32_e32 v44, 0xffff0000, v12
	v_lshlrev_b32_e32 v46, 16, v13
	v_and_b32_e32 v47, 0xffff0000, v13
	s_waitcnt lgkmcnt(0)
	v_sub_f32_e32 v11, v11, v180
	v_sub_f32_e32 v10, v10, v180
	v_sub_f32_e32 v13, v41, v180
	v_sub_f32_e32 v12, v40, v180
	v_pk_mul_f32 v[12:13], v[180:181], v[12:13] op_sel:[1,0]
	v_pk_mul_f32 v[10:11], v[180:181], v[10:11] op_sel:[1,0]
	s_waitcnt vmcnt(5)
	v_pk_fma_f32 v[20:21], v[198:199], v[10:11], v[206:207]
	v_pk_fma_f32 v[10:11], v[196:197], v[12:13], v[204:205]
	v_sub_f32_e32 v13, v47, v180
	v_sub_f32_e32 v12, v46, v180
	v_sub_f32_e32 v19, v44, v180
	v_sub_f32_e32 v18, v43, v180
	v_pk_mul_f32 v[18:19], v[180:181], v[18:19] op_sel:[1,0]
	v_pk_mul_f32 v[12:13], v[180:181], v[12:13] op_sel:[1,0]
	v_cvt_pk_bf16_f32 v10, v10, v11
	v_pk_fma_f32 v[16:17], v[194:195], v[12:13], v[202:203]
	v_pk_fma_f32 v[12:13], v[192:193], v[18:19], v[200:201]
	v_cvt_pk_bf16_f32 v11, v20, v21
	v_cvt_pk_bf16_f32 v12, v12, v13
	v_cvt_pk_bf16_f32 v13, v16, v17
	v_mad_u64_u32 v[14:15], s[18:19], v30, s89, v[0:1]
	ds_write_b128 v14, v[10:13] offset:36864
	s_or_b64 exec, exec, s[16:17]
	s_and_saveexec_b64 s[16:17], s[42:43]
	s_cbranch_execz .LBB0_486
.LBB0_509:
	v_lshlrev_b32_e32 v28, 16, v6
	v_and_b32_e32 v29, 0xffff0000, v6
	v_lshlrev_b32_e32 v6, 16, v7
	v_and_b32_e32 v7, 0xffff0000, v7
	v_lshlrev_b32_e32 v32, 16, v8
	v_and_b32_e32 v33, 0xffff0000, v8
	v_lshlrev_b32_e32 v39, 16, v9
	v_and_b32_e32 v40, 0xffff0000, v9
	s_waitcnt lgkmcnt(0)
	v_sub_f32_e32 v7, v7, v182
	v_sub_f32_e32 v6, v6, v182
	v_sub_f32_e32 v9, v29, v182
	v_sub_f32_e32 v8, v28, v182
	v_pk_mul_f32 v[8:9], v[182:183], v[8:9] op_sel:[1,0]
	v_pk_mul_f32 v[6:7], v[182:183], v[6:7] op_sel:[1,0]
	s_waitcnt vmcnt(5)
	v_pk_fma_f32 v[16:17], v[198:199], v[6:7], v[206:207]
	v_pk_fma_f32 v[6:7], v[196:197], v[8:9], v[204:205]
	v_sub_f32_e32 v9, v40, v182
	v_sub_f32_e32 v8, v39, v182
	v_sub_f32_e32 v15, v33, v182
	v_sub_f32_e32 v14, v32, v182
	v_pk_mul_f32 v[14:15], v[182:183], v[14:15] op_sel:[1,0]
	v_pk_mul_f32 v[8:9], v[182:183], v[8:9] op_sel:[1,0]
	v_cvt_pk_bf16_f32 v6, v6, v7
	v_pk_fma_f32 v[12:13], v[194:195], v[8:9], v[202:203]
	v_pk_fma_f32 v[8:9], v[192:193], v[14:15], v[200:201]
	v_cvt_pk_bf16_f32 v7, v16, v17
	v_cvt_pk_bf16_f32 v8, v8, v9
	v_cvt_pk_bf16_f32 v9, v12, v13
	v_mad_u64_u32 v[10:11], s[18:19], v38, s89, v[0:1]
	ds_write_b128 v10, v[6:9] offset:55296
	s_or_b64 exec, exec, s[16:17]
	s_and_saveexec_b64 s[16:17], s[40:41]
	s_cbranch_execnz .LBB0_487
	s_branch .LBB0_488
